# v12 plus: B loop next-tile ds_write hoisted ahead of the last four PV MFMAs
# baseline (speedup 1.0000x reference)
; #define MFMA(a, b, c) __builtin_amdgcn_mfma_f32_32x32x16_bf16((a), (b), (c), 0, 0, 0)
; __device__ __forceinline__ unsigned pk2(float lo, float hi) { const f32x2_t f = {lo, hi}; const bf16x2_t b = __builtin_convertvector(f, bf16x2_t); return __builtin_bit_cast(unsigned, b); }
; template <int DV>
; __device__ __forceinline__ void attn_tile(const unsigned char* Kl, const unsigned char* Vl, const bf16x8 (&qf)[4], f32x16 (&O)[DV / 32], float& m, float& l,
;                                           int l31, int hh, bool domask, int qpos, int kpos0) {
;     ...
;     float ps = 0.f;
; #pragma unroll
;     for (int sub = 0; sub < 2; sub++)
; #pragma unroll
;         for (int r = 0; r < 16; r++) { S[sub][r] = __builtin_amdgcn_exp2f(__builtin_fmaf(S[sub][r], SL2, -m)); ps += S[sub][r]; }
;     l += ps;
;     bf16x8 pb[2][2];
; #pragma unroll
;     for (int sub = 0; sub < 2; sub++)
; #pragma unroll
;         for (int s = 0; s < 2; s++) {
;             u32x4 cv;
;             cv[0] = pk2(S[sub][8 * s + 0], S[sub][8 * s + 1]); cv[1] = pk2(S[sub][8 * s + 2], S[sub][8 * s + 3]);
;             cv[2] = pk2(S[sub][8 * s + 4], S[sub][8 * s + 5]); cv[3] = pk2(S[sub][8 * s + 6], S[sub][8 * s + 7]);
;             pb[sub][s] = __builtin_bit_cast(bf16x8, cv);
;         }
; #pragma unroll
;     for (int sub = 0; sub < 2; sub++)
; #pragma unroll
;         for (int s = 0; s < 2; s++)
; #pragma unroll
;             for (int dt = 0; dt < DV / 32; dt++) {
;                 const bf16x8 vf = *(const bf16x8*)(Vl + (dt * 32 + l31) * LROW + (sub * 4 + s * 2 + hh) * 16);
;                 O[dt] = MFMA(vf, pb[sub][s], O[dt]);
;             }
; template <bool DIFF>
; __device__ __forceinline__ void attn_unit(const Params& p, int layer, int mode, int bl, int hidx, int qblk, bool isctx, unsigned char* lds) {
;     ...
;         if (more) {
;             unsigned char* wb = lds + ((it + 1) & 1) * BUFB + lr * LROW + lc * 16;
; #pragma unroll
;             for (int i = 0; i < NKM; i++) *(u32x4*)(wb + i * 9216) = kr[i];
; #pragma unroll
;             for (int i = 0; i < DV / 64; i++) *(u32x4*)(wb + KBYTES + i * 64 * LROW) = vr[i];
;         }
;         __syncthreads();
.LBB0_498:
	v_fma_f32 v96, v96, s28, -v148
	v_fma_f32 v97, v97, s28, -v148
	v_exp_f32_e32 v96, v96
	v_fma_f32 v98, v98, s28, -v148
	v_exp_f32_e32 v97, v97
	v_fma_f32 v99, v99, s28, -v148
	v_exp_f32_e32 v98, v98
	v_fma_f32 v100, v100, s28, -v148
	v_exp_f32_e32 v99, v99
	v_fma_f32 v101, v101, s28, -v148
	v_exp_f32_e32 v100, v100
	v_fma_f32 v102, v102, s28, -v148
	v_exp_f32_e32 v101, v101
	v_fma_f32 v103, v103, s28, -v148
	v_exp_f32_e32 v102, v102
	v_cvt_pk_bf16_f32 v164, v96, v97
	v_exp_f32_e32 v103, v103
	v_cvt_pk_bf16_f32 v165, v98, v99
	v_add_f32_e32 v14, v97, v96
	v_cvt_pk_bf16_f32 v166, v100, v101
	v_add_f32_e32 v14, v98, v14
	v_add_f32_e32 v14, v99, v14
	v_cvt_pk_bf16_f32 v167, v102, v103
	v_add_f32_e32 v14, v100, v14
	v_add_f32_e32 v14, v101, v14
	v_mfma_f32_32x32x16_bf16 v[64:79], v[226:229], v[164:167], v[64:79]
	v_fma_f32 v104, v104, s28, -v148
	v_fma_f32 v105, v105, s28, -v148
	v_exp_f32_e32 v104, v104
	v_fma_f32 v106, v106, s28, -v148
	v_exp_f32_e32 v105, v105
	v_fma_f32 v107, v107, s28, -v148
	v_exp_f32_e32 v106, v106
	s_waitcnt lgkmcnt(14)
	v_mfma_f32_32x32x16_bf16 v[48:63], v[230:233], v[164:167], v[48:63]
	v_fma_f32 v108, v108, s28, -v148
	v_exp_f32_e32 v107, v107
	v_fma_f32 v109, v109, s28, -v148
	v_exp_f32_e32 v108, v108
	v_fma_f32 v110, v110, s28, -v148
	v_exp_f32_e32 v109, v109
	v_fma_f32 v111, v111, s28, -v148
	s_waitcnt lgkmcnt(13)
	v_mfma_f32_32x32x16_bf16 v[32:47], v[234:237], v[164:167], v[32:47]
	v_exp_f32_e32 v110, v110
	v_add_f32_e32 v14, v102, v14
	v_exp_f32_e32 v111, v111
	v_add_f32_e32 v14, v103, v14
	v_cvt_pk_bf16_f32 v96, v104, v105
	v_cvt_pk_bf16_f32 v97, v106, v107
	v_add_f32_e32 v14, v104, v14
	s_waitcnt lgkmcnt(12)
	v_mfma_f32_32x32x16_bf16 v[16:31], v[238:241], v[164:167], v[16:31]
	v_add_f32_e32 v14, v105, v14
	v_cvt_pk_bf16_f32 v98, v108, v109
	v_add_f32_e32 v14, v106, v14
	v_cvt_pk_bf16_f32 v99, v110, v111
	v_add_f32_e32 v14, v107, v14
	v_add_f32_e32 v14, v108, v14
	v_add_f32_e32 v14, v109, v14
	s_waitcnt lgkmcnt(11)
	v_mfma_f32_32x32x16_bf16 v[64:79], v[242:245], v[96:99], v[64:79]
	v_fma_f32 v80, v80, s28, -v148
	v_fma_f32 v81, v81, s28, -v148
	v_exp_f32_e32 v80, v80
	v_fma_f32 v82, v82, s28, -v148
	v_exp_f32_e32 v81, v81
	v_fma_f32 v83, v83, s28, -v148
	v_exp_f32_e32 v82, v82
	s_waitcnt lgkmcnt(10)
	v_mfma_f32_32x32x16_bf16 v[48:63], v[246:249], v[96:99], v[48:63]
	v_fma_f32 v84, v84, s28, -v148
	v_exp_f32_e32 v83, v83
	v_fma_f32 v85, v85, s28, -v148
	v_exp_f32_e32 v84, v84
	v_fma_f32 v86, v86, s28, -v148
	v_exp_f32_e32 v85, v85
	v_fma_f32 v87, v87, s28, -v148
	s_waitcnt lgkmcnt(9)
	v_mfma_f32_32x32x16_bf16 v[32:47], v[156:159], v[96:99], v[32:47]
	v_exp_f32_e32 v86, v86
	v_add_f32_e32 v14, v110, v14
	v_exp_f32_e32 v87, v87
	v_add_f32_e32 v14, v111, v14
	v_cvt_pk_bf16_f32 v100, v80, v81
	v_cvt_pk_bf16_f32 v101, v82, v83
	v_add_f32_e32 v14, v80, v14
	s_waitcnt lgkmcnt(8)
	v_mfma_f32_32x32x16_bf16 v[16:31], v[160:163], v[96:99], v[16:31]
	v_add_f32_e32 v14, v81, v14
	v_cvt_pk_bf16_f32 v102, v84, v85
	v_add_f32_e32 v14, v82, v14
	v_cvt_pk_bf16_f32 v103, v86, v87
	v_add_f32_e32 v14, v83, v14
	v_add_f32_e32 v14, v84, v14
	v_add_f32_e32 v14, v85, v14
	s_waitcnt lgkmcnt(7)
	v_mfma_f32_32x32x16_bf16 v[64:79], v[194:197], v[100:103], v[64:79]
	v_fma_f32 v88, v88, s28, -v148
	v_fma_f32 v89, v89, s28, -v148
	v_exp_f32_e32 v88, v88
	v_fma_f32 v90, v90, s28, -v148
	v_exp_f32_e32 v89, v89
	v_fma_f32 v91, v91, s28, -v148
	v_exp_f32_e32 v90, v90
	s_waitcnt lgkmcnt(6)
	v_mfma_f32_32x32x16_bf16 v[48:63], v[198:201], v[100:103], v[48:63]
	v_fma_f32 v92, v92, s28, -v148
	v_exp_f32_e32 v91, v91
	v_fma_f32 v93, v93, s28, -v148
	v_exp_f32_e32 v92, v92
	v_fma_f32 v94, v94, s28, -v148
	v_exp_f32_e32 v93, v93
	v_fma_f32 v95, v95, s28, -v148
	s_waitcnt lgkmcnt(5)
	v_mfma_f32_32x32x16_bf16 v[32:47], v[202:205], v[100:103], v[32:47]
	v_exp_f32_e32 v94, v94
	v_add_f32_e32 v14, v86, v14
	v_exp_f32_e32 v95, v95
	v_add_f32_e32 v14, v87, v14
	v_cvt_pk_bf16_f32 v104, v88, v89
	v_cvt_pk_bf16_f32 v105, v90, v91
	v_add_f32_e32 v14, v88, v14
	s_waitcnt lgkmcnt(4)
	v_mfma_f32_32x32x16_bf16 v[16:31], v[206:209], v[100:103], v[16:31]
	v_add_f32_e32 v14, v89, v14
	v_cvt_pk_bf16_f32 v106, v92, v93
	v_add_f32_e32 v14, v90, v14
	v_cvt_pk_bf16_f32 v107, v94, v95
	v_add_f32_e32 v14, v91, v14
	v_add_f32_e32 v14, v92, v14
	v_add_f32_e32 v14, v93, v14
	s_add_i32 s24, s24, 1
	s_bitcmp1_b32 s24, 0
	s_cselect_b32 s8, 0x9000, 0
	s_add_i32 s1, s1, 64
	v_add_u32_e32 v0, s8, v147
	s_waitcnt vmcnt(3)
	ds_write_b128 v0, v[2:5]
	s_waitcnt vmcnt(2)
	ds_write_b128 v0, v[6:9] offset:9216
	s_waitcnt vmcnt(1)
	ds_write_b128 v0, v[10:13] offset:18432
	s_waitcnt vmcnt(0)
	ds_write_b128 v0, v[128:131] offset:27648
	s_waitcnt lgkmcnt(7)
	v_mfma_f32_32x32x16_bf16 v[64:79], v[210:213], v[104:107], v[64:79]
	v_add_f32_e32 v14, v94, v14
	v_add_f32_e32 v14, v95, v14
	s_waitcnt lgkmcnt(6)
	v_mfma_f32_32x32x16_bf16 v[48:63], v[214:217], v[104:107], v[48:63]
	v_add_f32_e32 v145, v145, v14
	s_cmp_eq_u32 s0, s24
	s_waitcnt lgkmcnt(0)
	s_barrier
	v_mfma_f32_32x32x16_bf16 v[32:47], v[218:221], v[104:107], v[32:47]
	v_mfma_f32_32x32x16_bf16 v[16:31], v[222:225], v[104:107], v[16:31]
	s_cbranch_scc1 .LBB0_501
